# attention units mapped to XCDs by token range (the XCD that produced q/k/v/gate for those tokens, and that will consume the output rows) instead of by head
# baseline (speedup 1.0000x reference)
; __device__ __forceinline__ float ex2(float x) { return __builtin_amdgcn_exp2f(x); }
; __device__ __forceinline__ float rcpf_(float x) { return __builtin_amdgcn_rcpf(x); }
; __device__ __forceinline__ int crow(int reg, int h) { return (reg & 3) + 8 * (reg >> 2) + 4 * h; }
; __device__ __forceinline__ void attn_phase(const Ptrs& P, int gw, int NGW, int lane) {
;     const bf16x8* QF = (const bf16x8*)(P.ws + WS_U1); const bf16x8* KF = QF + (size_t)M * AW / 8; const v2u* GF = (const v2u*)(KF + (size_t)M * AW / 8);
;     const bf16x8* VF = (const bf16x8*)(P.ws + WS_VT); bf16* OG = (bf16*)(P.ws + WS_OG);
;     const int r = lane & 31, hh = lane >> 5;
;     for (int u = gw; u < BATCH * AH * (SEQ / 32); u += NGW) {
;         const int qt = u & 127, bhh = u >> 7, b = bhh >> 4, h = bhh & 15;
;     ...
;             const bool diag = (kt == qt);
; #pragma unroll
;             for (int i = 0; i < 16; ++i) { float ff = rcpf_(1.0f + ex2(sa[i])), bt = 1.0f - ff;
;                 if (diag) { const bool valid = crow(i, hh) < r; bt = valid ? bt : 0.0f; ff = valid ? ff : 1.0f; }
.LBB0_635:
	s_cmp_lt_i32 s56, 7
	s_cselect_b64 s[4:5], -1, 0
	s_and_b64 s[38:39], s[4:5], s[2:3]
	s_andn2_b64 vcc, exec, s[38:39]
	s_cbranch_vccnz .LBB0_642
	s_cmpk_gt_i32 s60, 0x1fff
	s_cbranch_scc1 .LBB0_642
	s_waitcnt lgkmcnt(0)
	v_lshlrev_b32_e32 v185, 4, v232
	v_lshlrev_b32_e32 v233, 3, v232
	v_and_b32_e32 v234, 31, v232
	v_lshrrev_b32_e32 v235, 5, v232
	v_lshlrev_b32_e32 v236, 2, v235
	v_lshlrev_b32_e32 v238, 4, v235
	v_cmp_lt_u32_e64 s[4:5], v236, v234
	v_or_b32_e32 v237, 1, v236
	v_cmp_lt_u32_e64 s[6:7], v237, v234
	v_or_b32_e32 v237, 2, v236
	v_cmp_lt_u32_e64 s[8:9], v237, v234
	v_or_b32_e32 v237, 3, v236
	v_cmp_lt_u32_e64 s[10:11], v237, v234
	v_or_b32_e32 v237, 8, v236
	v_cmp_lt_u32_e64 s[12:13], v237, v234
	v_or_b32_e32 v237, 9, v236
	v_cmp_lt_u32_e64 s[14:15], v237, v234
	v_or_b32_e32 v237, 10, v236
	v_cmp_lt_u32_e64 s[16:17], v237, v234
	v_or_b32_e32 v237, 11, v236
	v_cmp_lt_u32_e64 s[18:19], v237, v234
	v_or_b32_e32 v237, 16, v236
	v_cmp_lt_u32_e64 s[20:21], v237, v234
	v_or_b32_e32 v237, 17, v236
	v_cmp_lt_u32_e64 s[22:23], v237, v234
	v_or_b32_e32 v237, 18, v236
	v_cmp_lt_u32_e64 s[24:25], v237, v234
	v_or_b32_e32 v237, 19, v236
	v_cmp_lt_u32_e64 s[26:27], v237, v234
	v_or_b32_e32 v237, 24, v236
	v_cmp_lt_u32_e64 s[28:29], v237, v234
	v_or_b32_e32 v237, 25, v236
	v_cmp_lt_u32_e64 s[30:31], v237, v234
	v_or_b32_e32 v237, 26, v236
	v_cmp_lt_u32_e64 s[34:35], v237, v234
	v_or_b32_e32 v237, 27, v236
	v_cmp_lt_u32_e64 s[36:37], v237, v234
	v_cmp_gt_u32_e64 s[2:3], 32, v232
	s_add_u32 s44, s54, 0x3800000
	s_addc_u32 s45, s55, 0
	s_add_u32 s46, s54, 0x5800000
	s_addc_u32 s47, s55, 0
	s_add_u32 s48, s54, 0x9c00000
	s_addc_u32 s49, s55, 0
	s_add_u32 s50, s54, 0x7800000
	s_addc_u32 s51, s55, 0
	s_add_u32 s42, s54, 0xbc00000
	s_addc_u32 s43, s55, 0
	s_mov_b32 s58, s60
	s_mov_b32 s83, s62
	s_movk_i32 s85, 0x2000
	s_cmpk_lg_i32 s64, 0x100
	s_cbranch_scc1 .Lp6_nomap
	s_bfe_u32 s78, s33, 0x20001
	s_lshl_b32 s78, s78, 11
	s_bfe_u32 s79, s33, 0x20006
	s_lshl_b32 s79, s79, 7
	s_or_b32 s78, s78, s79
	s_and_b32 s79, s33, 1
	s_lshl_b32 s79, s79, 6
	s_or_b32 s78, s78, s79
	s_bfe_u32 s79, s33, 0x30003
	s_lshl_b32 s79, s79, 3
	s_or_b32 s78, s78, s79
	s_and_b32 s79, s60, 7
	s_or_b32 s58, s78, s79
	s_movk_i32 s83, 0x200
	s_add_i32 s85, s58, 0x800

; __device__ __forceinline__ void attn_phase(const Ptrs& P, int gw, int NGW, int lane) {
;     ...
;     for (int u = gw; u < BATCH * AH * (SEQ / 32); u += NGW) {
;         const int qt = u & 127, bhh = u >> 7, b = bhh >> 4, h = bhh & 15;
;         const size_t rowbase = (size_t)b * SEQ;
;         bf16x8 qf[4], kf[4];
;         { const bf16x8* qp = QF + (size_t)(bhh * 128 + qt) * 256 + lane;
; #pragma unroll
;           for (int ks = 0; ks < 4; ++ks) qf[ks] = qp[ks * 64]; }
;         const bf16x8* kbase = KF + (size_t)bhh * 128 * 256 + lane;
;         const bf16x8* vbase = VF + (size_t)bhh * 128 * 256 + lane;
;         bf16x8 k1[4], k2[4], vf[2][2], v1[2][2];
;         { const int q1 = qt > 0 ? qt - 1 : 0, q2 = qt > 1 ? qt - 2 : 0;
; #pragma unroll
;           for (int ks = 0; ks < 4; ++ks) { kf[ks] = kbase[(size_t)qt * 256 + ks * 64]; k1[ks] = kbase[(size_t)q1 * 256 + ks * 64]; k2[ks] = kbase[(size_t)q2 * 256 + ks * 64]; }
; #pragma unroll
;           for (int dt = 0; dt < 2; ++dt)
; #pragma unroll
;               for (int s = 0; s < 2; ++s) { vf[dt][s] = vbase[(size_t)qt * 256 + (dt * 2 + s) * 64]; v1[dt][s] = vbase[(size_t)q1 * 256 + (dt * 2 + s) * 64]; } }
;         v2u gq_[8];
;         { const v2u* gp_ = GF + (size_t)(bhh * 128 + qt) * 512 + lane;
; #pragma unroll
;           for (int j = 0; j < 8; ++j) gq_[j] = gp_[j * 64]; }
;     ...
;         const size_t row = rowbase + qt * 32 + r;
;         bf16* op = OG + row * AW + h * HD + 8 * hh;
.Lp6_epi:
	s_lshr_b32 s80, s69, 4
	s_lshl_b32 s80, s80, 12
	s_lshl_b32 s81, s63, 5
	s_or_b32 s80, s80, s81
	v_or_b32_e32 v239, s80, v234
	v_lshlrev_b32_e32 v239, 11, v239
	s_and_b32 s81, s69, 15
	s_lshl_b32 s81, s81, 7
	v_add3_u32 v239, v239, s81, v238
	s_add_i32 s58, s58, s83
	s_cmp_lt_i32 s58, s85
	s_cselect_b32 s82, 1, 0
	s_waitcnt vmcnt(16)
	v_mov_b32_e32 v187, v160
	v_mov_b32_e32 v188, v161
	v_mov_b32_e32 v189, v162
	v_mov_b32_e32 v190, v163
	v_mov_b32_e32 v191, v164
	v_mov_b32_e32 v192, v165
	v_mov_b32_e32 v193, v166
	v_mov_b32_e32 v194, v167
	v_mov_b32_e32 v195, v168
	v_mov_b32_e32 v196, v169
	v_mov_b32_e32 v197, v170
	v_mov_b32_e32 v198, v171
	v_mov_b32_e32 v199, v172
	v_mov_b32_e32 v200, v173
	v_mov_b32_e32 v201, v174
	v_mov_b32_e32 v202, v175
	s_cmp_eq_u32 s82, 0
	s_cbranch_scc1 .Lp6_epi_compute
	s_and_b32 s63, s58, 0x7f
	s_lshr_b32 s69, s58, 7
	s_lshl_b32 s78, s58, 12
	s_add_u32 s74, s44, s78
	s_addc_u32 s75, s45, 0
	s_add_u32 s76, s50, s78
	s_addc_u32 s77, s51, 0
	global_load_dwordx4 v[48:51], v185, s[74:75]
	global_load_dwordx4 v[52:55], v185, s[74:75] offset:1024
	global_load_dwordx4 v[56:59], v185, s[74:75] offset:2048
	global_load_dwordx4 v[60:63], v185, s[74:75] offset:3072
	global_load_dwordx2 v[160:161], v233, s[76:77]
	global_load_dwordx2 v[162:163], v233, s[76:77] offset:512
	global_load_dwordx2 v[164:165], v233, s[76:77] offset:1024
	global_load_dwordx2 v[166:167], v233, s[76:77] offset:1536
	global_load_dwordx2 v[168:169], v233, s[76:77] offset:2048
	global_load_dwordx2 v[170:171], v233, s[76:77] offset:2560
	global_load_dwordx2 v[172:173], v233, s[76:77] offset:3072
	global_load_dwordx2 v[174:175], v233, s[76:77] offset:3584
	s_lshl_b32 s78, s69, 19
	s_add_u32 s70, s46, s78
	s_addc_u32 s71, s47, 0
	s_add_u32 s72, s48, s78
	s_addc_u32 s73, s49, 0
	s_lshl_b32 s78, s63, 12
	s_add_u32 s74, s70, s78
	s_addc_u32 s75, s71, 0
	s_add_u32 s76, s72, s78
	s_addc_u32 s77, s73, 0
	global_load_dwordx4 v[64:67], v185, s[74:75]
	global_load_dwordx4 v[68:71], v185, s[74:75] offset:1024
	global_load_dwordx4 v[72:75], v185, s[74:75] offset:2048
	global_load_dwordx4 v[76:79], v185, s[74:75] offset:3072
	global_load_dwordx4 v[80:83], v185, s[76:77]
	global_load_dwordx4 v[84:87], v185, s[76:77] offset:1024
	global_load_dwordx4 v[88:91], v185, s[76:77] offset:2048
	global_load_dwordx4 v[92:95], v185, s[76:77] offset:3072
	s_sub_i32 s78, s63, 1
	s_max_i32 s78, s78, 0
	s_lshl_b32 s78, s78, 12
	s_add_u32 s74, s70, s78
	s_addc_u32 s75, s71, 0
	s_add_u32 s76, s72, s78
	s_addc_u32 s77, s73, 0
	global_load_dwordx4 v[96:99], v185, s[74:75]
	global_load_dwordx4 v[100:103], v185, s[74:75] offset:1024
	global_load_dwordx4 v[104:107], v185, s[74:75] offset:2048
	global_load_dwordx4 v[108:111], v185, s[74:75] offset:3072
	global_load_dwordx4 v[112:115], v185, s[76:77]
	global_load_dwordx4 v[116:119], v185, s[76:77] offset:1024
	global_load_dwordx4 v[120:123], v185, s[76:77] offset:2048
	global_load_dwordx4 v[124:127], v185, s[76:77] offset:3072
	s_sub_i32 s78, s63, 2
	s_max_i32 s78, s78, 0
	s_lshl_b32 s78, s78, 12
	s_add_u32 s74, s70, s78
	s_addc_u32 s75, s71, 0
	s_add_u32 s76, s72, s78
	s_addc_u32 s77, s73, 0
	global_load_dwordx4 v[128:131], v185, s[74:75]
	global_load_dwordx4 v[132:135], v185, s[74:75] offset:1024
	global_load_dwordx4 v[136:139], v185, s[74:75] offset:2048
	global_load_dwordx4 v[140:143], v185, s[74:75] offset:3072
	global_load_dwordx4 v[144:147], v185, s[76:77]
	global_load_dwordx4 v[148:151], v185, s[76:77] offset:1024
	global_load_dwordx4 v[152:155], v185, s[76:77] offset:2048
	global_load_dwordx4 v[156:159], v185, s[76:77] offset:3072
